# k20 + S4: norm_w table load of each unit issued together with the dt/acl loads (consumed after the block's own wait)
# baseline (speedup 1.0000x reference)
.LBB0_1536:
	s_bfe_u32 s55, s74, 0x60003
	s_lshl_b32 s0, s74, 4
	s_and_b32 s0, s0, 0xffffe000
	s_lshl_b32 s1, s55, 7
	s_or_b32 s20, s1, s0
	s_and_b32 s54, s74, 7
	s_ashr_i32 s21, s20, 31
	s_lshl_b32 s56, s54, 2
	s_lshl_b64 s[0:1], s[20:21], 13
	s_add_u32 s0, s24, s0
	s_addc_u32 s1, s25, s1
	s_lshl_b32 s53, s54, 8
	s_add_u32 s2, s0, s53
	s_addc_u32 s3, s1, 0
	s_add_u32 s0, s2, 0x1000
	s_addc_u32 s1, s3, 0
	s_add_u32 s2, s2, 0x1800
	s_addc_u32 s3, s3, 0
	s_lshl_b32 s12, s44, 10
	s_add_i32 s22, s12, s45
	s_mov_b32 s23, m0
	s_mov_b32 m0, s22
	s_nop 0
	global_load_lds_dwordx4 v1, s[0:1]
	s_mov_b32 m0, s23
	s_add_i32 s22, 0, 0x18000
	s_add_i32 s12, s12, s22
	s_mov_b32 s23, m0
	s_mov_b32 m0, s12
	s_nop 0
	global_load_lds_dwordx4 v1, s[2:3]
	s_mov_b32 m0, s23
	s_lshl_b32 s12, s46, 10
	s_add_i32 s23, s12, s45
	s_mov_b32 s57, m0
	s_mov_b32 m0, s23
	s_nop 0
	global_load_lds_dwordx4 v180, s[0:1]
	s_mov_b32 m0, s57
	s_add_i32 s12, s12, s22
	s_mov_b32 s23, m0
	s_mov_b32 m0, s12
	s_nop 0
	global_load_lds_dwordx4 v180, s[2:3]
	s_mov_b32 m0, s23
	s_lshl_b32 s12, s47, 10
	s_add_i32 s23, s12, s45
	s_mov_b32 s57, m0
	s_mov_b32 m0, s23
	s_nop 0
	global_load_lds_dwordx4 v181, s[0:1]
	s_mov_b32 m0, s57
	s_add_i32 s12, s12, s22
	s_mov_b32 s23, m0
	s_mov_b32 m0, s12
	s_nop 0
	global_load_lds_dwordx4 v181, s[2:3]
	s_mov_b32 m0, s23
	s_lshl_b32 s12, s48, 10
	s_add_i32 s23, s12, s45
	s_mov_b32 s57, m0
	s_mov_b32 m0, s23
	s_nop 0
	global_load_lds_dwordx4 v182, s[0:1]
	s_mov_b32 m0, s57
	s_add_i32 s12, s12, s22
	s_mov_b32 s0, m0
	s_mov_b32 m0, s12
	s_nop 0
	global_load_lds_dwordx4 v182, s[2:3]
	s_mov_b32 m0, s0
	v_mov_b32_e32 v10, v0
	s_nop 0
	v_cmp_gt_i32_e32 vcc, 0x100, v10
	s_and_saveexec_b64 s[100:101], vcc
	v_lshl_add_u32 v16, s54, 8, v10
	v_readlane_b32 vcc_lo, v254, 10
	v_readlane_b32 vcc_hi, v254, 11
	v_ashrrev_i32_e32 v17, 31, v16
	s_nop 1
	v_lshl_add_u64 v[16:17], v[16:17], 2, vcc
	global_load_dword v18, v[16:17], off
	s_mov_b64 exec, s[100:101]
	v_cmp_gt_i32_e32 vcc, s49, v10
	s_and_saveexec_b64 s[2:3], vcc
	s_cbranch_execz .LBB0_1540
	v_add_u32_e32 v2, s20, v10
	v_ashrrev_i32_e32 v3, 31, v2
	v_lshlrev_b64 v[2:3], 7, v[2:3]
	v_lshl_add_u64 v[4:5], s[8:9], 0, v[2:3]
	s_lshl_b32 s12, s56, 2
	v_lshl_add_u64 v[2:3], s[10:11], 0, v[2:3]
	v_lshl_add_u64 v[4:5], v[4:5], 0, s[12:13]
	v_lshl_add_u64 v[6:7], v[2:3], 0, s[12:13]
	global_load_dwordx4 v[2:5], v[4:5], off
	s_nop 0
	global_load_dwordx4 v[6:9], v[6:7], off
	v_cmp_lt_i32_e32 vcc, 63, v10
	s_and_saveexec_b64 s[22:23], vcc
	s_cbranch_execz .LBB0_1539
	s_ashr_i32 s0, s20, 6
	s_ashr_i32 s1, s0, 31
	s_lshl_b64 s[0:1], s[0:1], 7
	s_add_u32 s0, s26, s0
	s_addc_u32 s1, s27, s1
	v_mov_b32_e32 v11, s12
	global_load_dwordx4 v[12:15], v11, s[0:1]
	s_waitcnt vmcnt(0)
	v_pk_add_f32 v[8:9], v[8:9], v[14:15]
	v_pk_add_f32 v[6:7], v[6:7], v[12:13]

.LBB0_1540:
	s_or_b64 exec, exec, s[2:3]
	s_movk_i32 s0, 0x100
	v_cmp_gt_i32_e32 vcc, s0, v10
	s_and_saveexec_b64 s[2:3], vcc
	s_cbranch_execz .LBB0_1542
	v_lshl_add_u32 v2, s54, 8, v10
	v_readlane_b32 s60, v254, 4
	v_ashrrev_i32_e32 v3, 31, v2
	v_readlane_b32 s66, v254, 10
	v_readlane_b32 s67, v254, 11
	v_readlane_b32 s64, v254, 8
	s_mov_b32 s64, s96
	v_lshl_add_u64 v[2:3], v[2:3], 2, s[66:67]
	s_nop 0
	v_lshl_add_u32 v3, v10, 2, 0
	v_add_u32_e32 v3, 0x22000, v3
	v_readlane_b32 s61, v254, 5
	v_readlane_b32 s62, v254, 6
	v_readlane_b32 s63, v254, 7
	v_readlane_b32 s65, v254, 9
	s_waitcnt vmcnt(0)
	ds_write_b32 v3, v18

.LBB0_1625:
	s_ashr_i32 s29, s28, 31
	s_lshl_b64 s[0:1], s[28:29], 20
	s_add_u32 s30, s33, s0
	s_addc_u32 s31, s42, s1
	s_and_b64 s[0:1], s[6:7], exec
	s_cselect_b32 s11, s31, s39
	s_cselect_b32 s29, s30, s38
	s_ashr_i32 s27, s26, 31
	s_lshl_b64 s[0:1], s[26:27], 20
	s_add_u32 s34, s43, s0
	s_addc_u32 s35, s44, s1
	s_and_b64 s[0:1], s[6:7], exec
	s_cselect_b32 s27, s35, s3
	s_cselect_b32 s56, s34, s2
	s_add_u32 s38, s38, 0x80080
	s_addc_u32 s39, s39, 0
	s_add_u32 s57, s2, 0x100
	v_mov_b32_e32 v2, 0
	s_addc_u32 s58, s3, 0
	s_mov_b32 s59, -2
	s_waitcnt lgkmcnt(0)
	v_mov_b32_e32 v3, v2
	v_mov_b32_e32 v4, v2
	v_mov_b32_e32 v5, v2
	v_mov_b32_e32 v6, v2
	v_mov_b32_e32 v7, v2
	v_mov_b32_e32 v8, v2
	v_mov_b32_e32 v9, v2
	v_mov_b32_e32 v18, v2
	v_mov_b32_e32 v19, v2
	v_mov_b32_e32 v20, v2
	v_mov_b32_e32 v21, v2
	v_mov_b32_e32 v22, v2
	v_mov_b32_e32 v23, v2
	v_mov_b32_e32 v24, v2
	v_mov_b32_e32 v25, v2
	v_mov_b32_e32 v34, v2
	v_mov_b32_e32 v35, v2
	v_mov_b32_e32 v36, v2
	v_mov_b32_e32 v37, v2
	v_mov_b32_e32 v38, v2
	v_mov_b32_e32 v39, v2
	v_mov_b32_e32 v40, v2
	v_mov_b32_e32 v41, v2
	v_mov_b32_e32 v50, v2
	v_mov_b32_e32 v51, v2
	v_mov_b32_e32 v52, v2
	v_mov_b32_e32 v53, v2
	v_mov_b32_e32 v54, v2
	v_mov_b32_e32 v55, v2
	v_mov_b32_e32 v56, v2
	v_mov_b32_e32 v57, v2
	v_mov_b32_e32 v10, v2
	v_mov_b32_e32 v11, v2
	v_mov_b32_e32 v12, v2
	v_mov_b32_e32 v13, v2
	v_mov_b32_e32 v14, v2
	v_mov_b32_e32 v15, v2
	v_mov_b32_e32 v16, v2
	v_mov_b32_e32 v17, v2
	v_mov_b32_e32 v26, v2
	v_mov_b32_e32 v27, v2
	v_mov_b32_e32 v28, v2
	v_mov_b32_e32 v29, v2
	v_mov_b32_e32 v30, v2
	v_mov_b32_e32 v31, v2
	v_mov_b32_e32 v32, v2
	v_mov_b32_e32 v33, v2
	v_mov_b32_e32 v42, v2
	v_mov_b32_e32 v43, v2
	v_mov_b32_e32 v44, v2
	v_mov_b32_e32 v45, v2
	v_mov_b32_e32 v46, v2
	v_mov_b32_e32 v47, v2
	v_mov_b32_e32 v48, v2
	v_mov_b32_e32 v49, v2
	v_mov_b32_e32 v58, v2
	v_mov_b32_e32 v59, v2
	v_mov_b32_e32 v60, v2
	v_mov_b32_e32 v61, v2
	v_mov_b32_e32 v62, v2
	v_mov_b32_e32 v63, v2
	v_mov_b32_e32 v64, v2
	v_mov_b32_e32 v65, v2
	v_mov_b32_e32 v66, v2
	v_mov_b32_e32 v67, v2
	v_mov_b32_e32 v68, v2
	v_mov_b32_e32 v69, v2
	v_mov_b32_e32 v70, v2
	v_mov_b32_e32 v71, v2
	v_mov_b32_e32 v72, v2
	v_mov_b32_e32 v73, v2
	v_mov_b32_e32 v82, v2
	v_mov_b32_e32 v83, v2
	v_mov_b32_e32 v84, v2
	v_mov_b32_e32 v85, v2
	v_mov_b32_e32 v86, v2
	v_mov_b32_e32 v87, v2
	v_mov_b32_e32 v88, v2
	v_mov_b32_e32 v89, v2
	v_mov_b32_e32 v98, v2
	v_mov_b32_e32 v99, v2
	v_mov_b32_e32 v100, v2
	v_mov_b32_e32 v101, v2
	v_mov_b32_e32 v102, v2
	v_mov_b32_e32 v103, v2
	v_mov_b32_e32 v104, v2
	v_mov_b32_e32 v105, v2
	v_mov_b32_e32 v114, v2
	v_mov_b32_e32 v115, v2
	v_mov_b32_e32 v116, v2
	v_mov_b32_e32 v117, v2
	v_mov_b32_e32 v118, v2
	v_mov_b32_e32 v119, v2
	v_mov_b32_e32 v120, v2
	v_mov_b32_e32 v121, v2
	v_mov_b32_e32 v74, v2
	v_mov_b32_e32 v75, v2
	v_mov_b32_e32 v76, v2
	v_mov_b32_e32 v77, v2
	v_mov_b32_e32 v78, v2
	v_mov_b32_e32 v79, v2
	v_mov_b32_e32 v80, v2
	v_mov_b32_e32 v81, v2
	v_mov_b32_e32 v90, v2
	v_mov_b32_e32 v91, v2
	v_mov_b32_e32 v92, v2
	v_mov_b32_e32 v93, v2
	v_mov_b32_e32 v94, v2
	v_mov_b32_e32 v95, v2
	v_mov_b32_e32 v96, v2
	v_mov_b32_e32 v97, v2
	v_mov_b32_e32 v106, v2
	v_mov_b32_e32 v107, v2
	v_mov_b32_e32 v108, v2
	v_mov_b32_e32 v109, v2
	v_mov_b32_e32 v110, v2
	v_mov_b32_e32 v111, v2
	v_mov_b32_e32 v112, v2
	v_mov_b32_e32 v113, v2
	v_mov_b32_e32 v122, v2
	v_mov_b32_e32 v123, v2
	v_mov_b32_e32 v124, v2
	v_mov_b32_e32 v125, v2
	v_mov_b32_e32 v126, v2
	v_mov_b32_e32 v127, v2
	v_mov_b32_e32 v128, v2
	v_mov_b32_e32 v129, v2
	s_nop 0
	s_nop 0
	s_nop 0
	s_nop 0
	s_nop 0
	s_nop 0
	s_nop 0
	s_nop 0
	s_nop 0
	s_nop 0
	s_nop 0
	s_nop 0
	s_nop 0
	s_nop 0
	s_nop 0
